# P4 epilogue: all 8 per-row rstd loads issued together (one round trip instead of two)
# speedup vs baseline: 1.0121x; 1.0121x over previous
; #define PG8_LAS __attribute__((address_space(3)))
; #define PG8_LDW(BUF, N_, BJ_) do { const unsigned ch_ = (unsigned)((BJ_) * 2816 + c0 + colw + 4 * (N_)) * 4u; \
;             W[BUF][0] = *(const f32x4*)((const char*)cw + ch_); W[BUF][1] = *(const f32x4*)((const char*)cw + 5632u * 4u + ch_); \
;             W[BUF][2] = *(const f32x4*)((const char*)cw + 2u * 5632u * 4u + ch_); W[BUF][3] = *(const f32x4*)((const char*)cb + ch_); } while (0)
;     __device__ __forceinline__ void operator()(f32x4 (&acc)[2][2][4][2], const Unit& u, int wr, int wc, int fr_, int fq_) const {
;     ...
;             for (int m = 0; m < 4; ++m) { const int r = row0 + ai * HALF + m * 16; const float rs = *(const float*)((const char*)PS + (unsigned)r * 4u);
; #pragma unroll
;                 for (int bj = 0; bj < 2; ++bj)
; #pragma unroll
;                     for (int n = 0; n < 2; ++n) acc[ai][bj][m][n] = acc[ai][bj][m][n] * rs;
;                 asm volatile("" ::: "memory"); __builtin_amdgcn_sched_barrier(0); }
;         f32x4 W[2][4];
;     ...
;         PG8_LDW(0, 0, 0);
;         if (fr >= 14) {
; #pragma unroll
;             for (int ai = 0; ai < 2; ++ai)
; #pragma unroll
;                 for (int bj = 0; bj < 2; ++bj)
; #pragma unroll
;                     for (int n = 0; n < 2; ++n) *(PG8_LAS f32x4*)(hal + (((ai * 2 + wr) * 2 + (fr - 14)) * 256 + bj * 128 + colw + 4 * n)) = acc[ai][bj][3][n];
;             if (wr == 1) {
; #pragma unroll
;                 for (int bj = 0; bj < 2; ++bj)
; #pragma unroll
;                     for (int n = 0; n < 2; ++n) *(f32x4*)(HALO4 + (size_t)(u.pm * 4 + 2 + (fr - 14)) * 5632 + bj * 2816 + c0 + colw + 4 * n) = acc[1][bj][3][n]; }
.LBB0_663:
	s_lshl_b32 s1, s8, 8
	v_mov_b32_e32 v165, v179
	v_mov_b32_e32 v130, v181
	s_add_i32 s1, s1, s45
	s_nop 0
	v_add_u32_e32 v225, s1, v165
	v_lshlrev_b32_e32 v135, 2, v225
	global_load_dword v164, v135, s[12:13]
	v_lshl_add_u32 v154, v130, 3, s46
	v_add_u32_e32 v130, 64, v135
	global_load_dword v194, v130, s[12:13]
	v_add_u32_e32 v130, 0x80, v135
	global_load_dword v192, v130, s[12:13]
	v_add_u32_e32 v130, 0xc0, v135
	global_load_dword v134, v130, s[12:13]
	v_add_u32_e32 v130, 0x200, v135
	global_load_dword v200, v130, s[12:13]
	v_add_u32_e32 v130, 0x240, v135
	global_load_dword v198, v130, s[12:13]
	v_add_u32_e32 v130, 0x280, v135
	global_load_dword v196, v130, s[12:13]
	v_add_u32_e32 v130, 0x2c0, v135
	global_load_dword v248, v130, s[12:13]
	s_waitcnt vmcnt(4)
	v_pk_mul_f32 v[158:159], v[128:129], v[134:135] op_sel_hi:[1,0]
	v_pk_mul_f32 v[156:157], v[126:127], v[134:135] op_sel_hi:[1,0]
	v_pk_mul_f32 v[64:65], v[64:65], v[134:135] op_sel_hi:[1,0]
	v_pk_mul_f32 v[62:63], v[62:63], v[134:135] op_sel_hi:[1,0]
	v_pk_mul_f32 v[132:133], v[112:113], v[134:135] op_sel_hi:[1,0]
	v_pk_mul_f32 v[130:131], v[110:111], v[134:135] op_sel_hi:[1,0]
	v_pk_mul_f32 v[48:49], v[48:49], v[134:135] op_sel_hi:[1,0]
	v_pk_mul_f32 v[46:47], v[46:47], v[134:135] op_sel_hi:[1,0]
	s_waitcnt vmcnt(0)
	v_pk_mul_f32 v[140:141], v[92:93], v[248:249] op_sel_hi:[1,0]
	v_pk_mul_f32 v[138:139], v[90:91], v[248:249] op_sel_hi:[1,0]
	v_pk_mul_f32 v[60:61], v[60:61], v[248:249] op_sel_hi:[1,0]
	v_pk_mul_f32 v[58:59], v[58:59], v[248:249] op_sel_hi:[1,0]
	v_pk_mul_f32 v[112:113], v[80:81], v[248:249] op_sel_hi:[1,0]
	v_pk_mul_f32 v[110:111], v[78:79], v[248:249] op_sel_hi:[1,0]
	v_pk_mul_f32 v[36:37], v[36:37], v[248:249] op_sel_hi:[1,0]
	v_pk_mul_f32 v[34:35], v[34:35], v[248:249] op_sel_hi:[1,0]
	s_lshl_b32 s38, s0, 7
	v_add_u32_e32 v190, s38, v154
	v_lshlrev_b32_e32 v176, 2, v190
	global_load_dwordx4 v[146:149], v176, s[22:23]
	global_load_dwordx4 v[150:153], v176, s[24:25]
	global_load_dwordx4 v[142:145], v176, s[86:87]
	global_load_dwordx4 v[90:93], v176, s[88:89]
	v_cndmask_b32_e64 v78, 0, 1, s[14:15]
	v_cmp_lt_i32_e32 vcc, 13, v165
	v_lshlrev_b32_e32 v193, 2, v154
	v_cmp_ne_u32_e64 s[0:1], 1, v78
	s_and_saveexec_b64 s[36:37], vcc
	s_cbranch_execz .LBB0_666
	v_add_lshl_u32 v78, s49, v165, 10
	s_add_i32 s9, 0, 0x20000
	v_add3_u32 v79, s9, v78, v193
	s_add_i32 s9, 0, 0x21000
	v_add3_u32 v78, s9, v78, v193
	s_and_b64 vcc, exec, s[0:1]
	ds_write_b128 v79, v[156:159]
	ds_write_b128 v79, v[62:65] offset:16
	ds_write_b128 v79, v[130:133] offset:512
	ds_write_b128 v79, v[46:49] offset:528
	ds_write_b128 v78, v[138:141]
	ds_write_b128 v79, v[58:61] offset:4112
	ds_write_b128 v79, v[110:113] offset:4608
	ds_write_b128 v79, v[34:37] offset:4624
	s_cbranch_vccnz .LBB0_666
	s_lshl_b32 s9, s8, 2
	v_add3_u32 v80, s9, -12, v165
	v_mov_b64_e32 v[78:79], s[10:11]
	s_ashr_i32 s39, s38, 31
	v_mad_i64_i32 v[78:79], s[40:41], v80, s55, v[78:79]
	v_ashrrev_i32_e32 v155, 31, v154
	v_lshl_add_u64 v[78:79], s[38:39], 2, v[78:79]
	v_lshl_add_u64 v[78:79], v[154:155], 2, v[78:79]
	global_store_dwordx4 v[78:79], v[138:141], off
	global_store_dwordx4 v[78:79], v[58:61], off offset:16
	v_add_co_u32_e32 v78, vcc, 0x2000, v78
	s_nop 1
	v_addc_co_u32_e32 v79, vcc, 0, v79, vcc
	global_store_dwordx4 v[78:79], v[110:113], off offset:3072
	global_store_dwordx4 v[78:79], v[34:37], off offset:3088
